# channel-DFT GEMM: K-loop restricted to the single nonzero 128-wide diagonal block of the block-diagonal DFT weight (skips 3 of 4 K iterations that multiply exact zeros)
# speedup vs baseline: 1.0095x; 1.0095x over previous
.LBB0_1013:
	v_readlane_b32 s0, v252, 31
	s_add_u32 s25, s14, 0x100000
	v_mov_b32_e32 v14, v223
	v_readlane_b32 s1, v252, 32
	s_barrier
	s_addc_u32 s26, s15, 0
	s_and_b64 vcc, exec, s[0:1]
	v_readfirstlane_b32 s10, v14
	s_cbranch_vccnz .LBB0_1161
	v_lshlrev_b32_e32 v0, 4, v14
	v_add_u32_e32 v1, 0x2000, v0
	v_ashrrev_i32_e32 v2, 31, v1
	v_lshrrev_b32_e32 v2, 22, v2
	v_add_u32_e32 v2, v1, v2
	v_ashrrev_i32_e32 v8, 10, v2
	v_mul_i32_i24_e32 v3, 0x400, v8
	v_sub_u32_e32 v1, v1, v3
	v_lshrrev_b32_e32 v3, 4, v1
	v_bitop3_b32 v1, v3, v1, 32 bitop3:0x6c
	v_ashrrev_i32_e32 v3, 31, v1
	v_lshrrev_b32_e32 v3, 26, v3
	v_add_u32_e32 v3, v1, v3
	v_ashrrev_i32_e32 v9, 6, v3
	v_and_b32_e32 v3, 0xc0, v3
	v_sub_u32_e32 v1, v1, v3
	v_lshlrev_b32_e32 v2, 5, v8
	v_ashrrev_i16_sdwa v1, v218, sext(v1) dst_sel:DWORD dst_unused:UNUSED_PAD src0_sel:DWORD src1_sel:BYTE_0
	v_and_b32_e32 v2, 32, v2
	v_bfe_i32 v10, v1, 0, 16
	v_add_u32_e32 v1, v2, v10
	v_lshlrev_b32_e32 v2, 3, v8
	v_and_b32_e32 v2, 0x3ffff0, v2
	v_add_lshl_u32 v2, v9, v2, 10
	v_lshl_add_u32 v128, v1, 1, v2
	v_bfe_i32 v2, v14, 27, 1
	v_lshrrev_b32_e32 v2, 22, v2
	v_add_u32_e32 v2, v0, v2
	v_and_b32_e32 v2, 0xfffffc00, v2
	v_sub_u32_e32 v0, v0, v2
	v_lshrrev_b32_e32 v2, 4, v0
	v_bitop3_b32 v0, v2, v0, 32 bitop3:0x6c
	v_ashrrev_i32_e32 v2, 31, v0
	v_ashrrev_i32_e32 v1, 31, v14
	v_lshrrev_b32_e32 v2, 26, v2
	v_lshrrev_b32_e32 v1, 26, v1
	v_add_u32_e32 v2, v0, v2
	v_add_u32_e32 v1, v14, v1
	v_ashrrev_i32_e32 v12, 6, v2
	v_and_b32_e32 v2, 0xc0, v2
	s_ashr_i32 s4, s10, 6
	v_ashrrev_i32_e32 v11, 6, v1
	v_sub_u32_e32 v0, v0, v2
	s_ashr_i32 s5, s10, 8
	s_lshl_b32 s27, s4, 10
	v_lshlrev_b32_e32 v1, 5, v11
	v_ashrrev_i16_sdwa v0, v218, sext(v0) dst_sel:DWORD dst_unused:UNUSED_PAD src0_sel:DWORD src1_sel:BYTE_0
	s_add_u32 s31, s14, 0xf900000
	v_and_b32_e32 v1, 32, v1
	v_bfe_i32 v13, v0, 0, 16
	s_addc_u32 s35, s15, 0
	v_add_u32_e32 v0, v1, v13
	v_lshlrev_b32_e32 v1, 3, v11
	v_readlane_b32 s0, v253, 29
	v_and_b32_e32 v1, 0x3ffff0, v1
	v_readlane_b32 s1, v253, 30
	s_add_u32 s12, s25, s0
	v_add_lshl_u32 v1, v12, v1, 10
	s_addc_u32 s13, s26, s1
	v_readlane_b32 s72, v252, 55
	s_lshl_b32 s72, s72, 8
	s_add_u32 s12, s12, s72
	s_addc_u32 s13, s13, 0
	s_add_i32 s50, s27, 0
	v_lshl_add_u32 v130, v0, 1, v1
	s_add_i32 m0, s50, 0x10000
	v_mov_b32_e32 v131, v209
	global_load_lds_dwordx4 v130, s[12:13]
	s_add_i32 m0, s50, 0x12000
	s_add_u32 s0, s12, 0x20000
	global_load_lds_dwordx4 v128, s[12:13]
	s_addc_u32 s1, s13, 0
	s_add_i32 m0, s50, 0x14000
	v_mov_b32_e32 v129, v209
	global_load_lds_dwordx4 v130, s[0:1]
	s_add_i32 m0, s50, 0x16000
	v_lshl_add_u64 v[6:7], s[12:13], 0, v[130:131]
	global_load_lds_dwordx4 v128, s[0:1]
	v_readlane_b32 s0, v253, 27
	v_readlane_b32 s1, v253, 28
	s_add_u32 s0, s31, s0
	s_addc_u32 s1, s35, s1
	s_add_u32 s0, s0, s72
	s_addc_u32 s1, s1, 0
	s_add_i32 s51, s50, 0x2000
	s_mov_b32 m0, s50
	s_add_u32 s22, s0, 0x20000
	global_load_lds_dwordx4 v130, s[0:1]
	s_mov_b32 m0, s51
	s_addc_u32 s23, s1, 0
	s_add_i32 s54, s50, 0x4000
	global_load_lds_dwordx4 v128, s[0:1]
	s_mov_b32 m0, s54
	s_add_i32 s55, s50, 0x6000
	global_load_lds_dwordx4 v130, s[22:23]
	s_mov_b32 m0, s55
	s_cmp_eq_u32 s5, 1
	global_load_lds_dwordx4 v128, s[22:23]
	v_lshl_add_u64 v[4:5], s[12:13], 0, v[128:129]
	v_lshl_add_u64 v[0:1], s[0:1], 0, v[130:131]
	s_cselect_b64 s[36:37], -1, 0
	s_cmp_lg_u32 s5, 1
	v_lshl_add_u64 v[2:3], s[0:1], 0, v[128:129]
	s_cbranch_scc1 .LBB0_1016
	s_barrier

.LBB0_1025:
	s_ashr_i32 s45, s44, 31
	s_lshl_b64 s[22:23], s[44:45], 18
	s_add_u32 s46, s31, s22
	s_addc_u32 s47, s35, s23
	s_and_b64 s[22:23], s[10:11], exec
	s_cselect_b32 s45, s47, s1
	s_cselect_b32 s67, s46, s0
	s_ashr_i32 s43, s42, 31
	s_lshl_b64 s[22:23], s[42:43], 18
	s_add_u32 s48, s25, s22
	s_addc_u32 s49, s26, s23
	s_and_b64 s[22:23], s[10:11], exec
	s_cselect_b32 s43, s49, s13
	s_cselect_b32 s68, s48, s12
	s_add_u32 s0, s0, 0x20080
	s_addc_u32 s1, s1, 0
	s_add_u32 s69, s12, 0x100
	v_mov_b32_e32 v0, 0
	s_addc_u32 s70, s13, 0
	s_mov_b32 s71, 4
	v_mov_b32_e32 v1, v0
	v_mov_b32_e32 v2, v0
	v_mov_b32_e32 v3, v0
	v_mov_b32_e32 v4, v0
	v_mov_b32_e32 v5, v0
	v_mov_b32_e32 v6, v0
	v_mov_b32_e32 v7, v0
	v_mov_b32_e32 v16, v0
	v_mov_b32_e32 v17, v0
	v_mov_b32_e32 v18, v0
	v_mov_b32_e32 v19, v0
	v_mov_b32_e32 v20, v0
	v_mov_b32_e32 v21, v0
	v_mov_b32_e32 v22, v0
	v_mov_b32_e32 v23, v0
	v_mov_b32_e32 v32, v0
	v_mov_b32_e32 v33, v0
	v_mov_b32_e32 v34, v0
	v_mov_b32_e32 v35, v0
	v_mov_b32_e32 v36, v0
	v_mov_b32_e32 v37, v0
	v_mov_b32_e32 v38, v0
	v_mov_b32_e32 v39, v0
	v_mov_b32_e32 v48, v0
	v_mov_b32_e32 v49, v0
	v_mov_b32_e32 v50, v0
	v_mov_b32_e32 v51, v0
	v_mov_b32_e32 v52, v0
	v_mov_b32_e32 v53, v0
	v_mov_b32_e32 v54, v0
	v_mov_b32_e32 v55, v0
	v_mov_b32_e32 v8, v0
	v_mov_b32_e32 v9, v0
	v_mov_b32_e32 v10, v0
	v_mov_b32_e32 v11, v0
	v_mov_b32_e32 v12, v0
	v_mov_b32_e32 v13, v0
	v_mov_b32_e32 v14, v0
	v_mov_b32_e32 v15, v0
	v_mov_b32_e32 v24, v0
	v_mov_b32_e32 v25, v0
	v_mov_b32_e32 v26, v0
	v_mov_b32_e32 v27, v0
	v_mov_b32_e32 v28, v0
	v_mov_b32_e32 v29, v0
	v_mov_b32_e32 v30, v0
	v_mov_b32_e32 v31, v0
	v_mov_b32_e32 v40, v0
	v_mov_b32_e32 v41, v0
	v_mov_b32_e32 v42, v0
	v_mov_b32_e32 v43, v0
	v_mov_b32_e32 v44, v0
	v_mov_b32_e32 v45, v0
	v_mov_b32_e32 v46, v0
	v_mov_b32_e32 v47, v0
	v_mov_b32_e32 v56, v0
	v_mov_b32_e32 v57, v0
	v_mov_b32_e32 v58, v0
	v_mov_b32_e32 v59, v0
	v_mov_b32_e32 v60, v0
	v_mov_b32_e32 v61, v0
	v_mov_b32_e32 v62, v0
	v_mov_b32_e32 v63, v0
	v_mov_b32_e32 v64, v0
	v_mov_b32_e32 v65, v0
	v_mov_b32_e32 v66, v0
	v_mov_b32_e32 v67, v0
	v_mov_b32_e32 v68, v0
	v_mov_b32_e32 v69, v0
	v_mov_b32_e32 v70, v0
	v_mov_b32_e32 v71, v0
	v_mov_b32_e32 v80, v0
	v_mov_b32_e32 v81, v0
	v_mov_b32_e32 v82, v0
	v_mov_b32_e32 v83, v0
	v_mov_b32_e32 v84, v0
	v_mov_b32_e32 v85, v0
	v_mov_b32_e32 v86, v0
	v_mov_b32_e32 v87, v0
	v_mov_b32_e32 v96, v0
	v_mov_b32_e32 v97, v0
	v_mov_b32_e32 v98, v0
	v_mov_b32_e32 v99, v0
	v_mov_b32_e32 v100, v0
	v_mov_b32_e32 v101, v0
	v_mov_b32_e32 v102, v0
	v_mov_b32_e32 v103, v0
	v_mov_b32_e32 v112, v0
	v_mov_b32_e32 v113, v0
	v_mov_b32_e32 v114, v0
	v_mov_b32_e32 v115, v0
	v_mov_b32_e32 v116, v0
	v_mov_b32_e32 v117, v0
	v_mov_b32_e32 v118, v0
	v_mov_b32_e32 v119, v0
	v_mov_b32_e32 v72, v0
	v_mov_b32_e32 v73, v0
	v_mov_b32_e32 v74, v0
	v_mov_b32_e32 v75, v0
	v_mov_b32_e32 v76, v0
	v_mov_b32_e32 v77, v0
	v_mov_b32_e32 v78, v0
	v_mov_b32_e32 v79, v0
	v_mov_b32_e32 v88, v0
	v_mov_b32_e32 v89, v0
	v_mov_b32_e32 v90, v0
	v_mov_b32_e32 v91, v0
	v_mov_b32_e32 v92, v0
	v_mov_b32_e32 v93, v0
	v_mov_b32_e32 v94, v0
	v_mov_b32_e32 v95, v0
	v_mov_b32_e32 v104, v0
	v_mov_b32_e32 v105, v0
	v_mov_b32_e32 v106, v0
	v_mov_b32_e32 v107, v0
	v_mov_b32_e32 v108, v0
	v_mov_b32_e32 v109, v0
	v_mov_b32_e32 v110, v0
	v_mov_b32_e32 v111, v0
	v_mov_b32_e32 v120, v0
	v_mov_b32_e32 v121, v0
	v_mov_b32_e32 v122, v0
	v_mov_b32_e32 v123, v0
	v_mov_b32_e32 v124, v0
	v_mov_b32_e32 v125, v0
	v_mov_b32_e32 v126, v0
	v_mov_b32_e32 v127, v0
